# hand-written software-pipelined GLU epilogue (6 chunks of ya0+z loads in flight, counted vmcnt) replacing the serialized compiler epilogue
# speedup vs baseline: 1.0316x; 1.0198x over previous
.LBB0_853:
	v_lshl_add_u32 v143, s44, 8, v146
	v_lshl_or_b32 v144, s35, 8, v148
	v_lshlrev_b32_e32 v145, 2, v144
	v_lshlrev_b32_e32 v140, 11, v143
	v_lshl_add_u32 v140, v144, 1, v140
	v_mov_b32_e32 v142, v140
	v_mul_u32_u24_e32 v141, s78, v143
	v_lshl_add_u32 v141, v144, 1, v141
	v_readlane_b32 s2, v251, 14
	v_readlane_b32 s3, v251, 15
	v_readlane_b32 s16, v253, 41
	v_readlane_b32 s17, v253, 42
	s_nop 4
	global_load_dwordx4 v[224:227], v145, s[4:5]
	global_load_dwordx4 v[228:231], v145, s[4:5] offset:16
	global_load_dwordx4 v[232:235], v145, s[4:5] offset:512
	global_load_dwordx4 v[236:239], v145, s[4:5] offset:528
	global_load_dwordx4 v[150:153], v140, s[52:53]
	global_load_dwordx4 v[154:157], v141, s[2:3] offset:2048
	global_load_dwordx4 v[158:161], v140, s[52:53] offset:256
	global_load_dwordx4 v[162:165], v141, s[2:3] offset:2304
	v_add_u32_e32 v140, 0x8000, v140
	v_add_u32_e32 v141, 0x6a000, v141
	global_load_dwordx4 v[166:169], v140, s[52:53]
	global_load_dwordx4 v[170:173], v141, s[2:3] offset:2048
	global_load_dwordx4 v[174:177], v140, s[52:53] offset:256
	global_load_dwordx4 v[178:181], v141, s[2:3] offset:2304
	v_add_u32_e32 v140, 0x8000, v140
	v_add_u32_e32 v141, 0x6a000, v141
	global_load_dwordx4 v[182:185], v140, s[52:53]
	global_load_dwordx4 v[186:189], v141, s[2:3] offset:2048
	global_load_dwordx4 v[190:193], v140, s[52:53] offset:256
	global_load_dwordx4 v[194:197], v141, s[2:3] offset:2304
	v_add_u32_e32 v140, 0x8000, v140
	v_add_u32_e32 v141, 0x6a000, v141
	s_waitcnt vmcnt(10)
	v_pk_add_f32 v[126:127], v[126:127], v[224:225]
	v_pk_add_f32 v[128:129], v[128:129], v[226:227]
	v_pk_add_f32 v[122:123], v[122:123], v[228:229]
	v_pk_add_f32 v[124:125], v[124:125], v[230:231]
	v_mul_f32_e32 v126, 0xbfb8aa3b, v126
	v_mul_f32_e32 v127, 0xbfb8aa3b, v127
	v_mul_f32_e32 v128, 0xbfb8aa3b, v128
	v_mul_f32_e32 v129, 0xbfb8aa3b, v129
	v_mul_f32_e32 v122, 0xbfb8aa3b, v122
	v_mul_f32_e32 v123, 0xbfb8aa3b, v123
	v_mul_f32_e32 v124, 0xbfb8aa3b, v124
	v_mul_f32_e32 v125, 0xbfb8aa3b, v125
	v_exp_f32_e32 v126, v126
	v_exp_f32_e32 v127, v127
	v_exp_f32_e32 v128, v128
	v_exp_f32_e32 v129, v129
	v_exp_f32_e32 v122, v122
	v_exp_f32_e32 v123, v123
	v_exp_f32_e32 v124, v124
	v_exp_f32_e32 v125, v125
	v_add_f32_e32 v126, 1.0, v126
	v_add_f32_e32 v127, 1.0, v127
	v_add_f32_e32 v128, 1.0, v128
	v_add_f32_e32 v129, 1.0, v129
	v_add_f32_e32 v122, 1.0, v122
	v_add_f32_e32 v123, 1.0, v123
	v_add_f32_e32 v124, 1.0, v124
	v_add_f32_e32 v125, 1.0, v125
	v_rcp_f32_e32 v126, v126
	v_rcp_f32_e32 v127, v127
	v_rcp_f32_e32 v128, v128
	v_rcp_f32_e32 v129, v129
	v_rcp_f32_e32 v122, v122
	v_rcp_f32_e32 v123, v123
	v_rcp_f32_e32 v124, v124
	v_rcp_f32_e32 v125, v125
	v_lshlrev_b32_e32 v143, 16, v150
	v_mul_f32_e32 v126, v126, v143
	v_lshlrev_b32_e32 v144, 16, v154
	v_mul_f32_e32 v126, v126, v144
	v_and_b32_e32 v143, 0xffff0000, v150
	v_mul_f32_e32 v127, v127, v143
	v_and_b32_e32 v144, 0xffff0000, v154
	v_mul_f32_e32 v127, v127, v144
	v_lshlrev_b32_e32 v143, 16, v151
	v_mul_f32_e32 v128, v128, v143
	v_lshlrev_b32_e32 v144, 16, v155
	v_mul_f32_e32 v128, v128, v144
	v_and_b32_e32 v143, 0xffff0000, v151
	v_mul_f32_e32 v129, v129, v143
	v_and_b32_e32 v144, 0xffff0000, v155
	v_mul_f32_e32 v129, v129, v144
	v_lshlrev_b32_e32 v143, 16, v152
	v_mul_f32_e32 v122, v122, v143
	v_lshlrev_b32_e32 v144, 16, v156
	v_mul_f32_e32 v122, v122, v144
	v_and_b32_e32 v143, 0xffff0000, v152
	v_mul_f32_e32 v123, v123, v143
	v_and_b32_e32 v144, 0xffff0000, v156
	v_mul_f32_e32 v123, v123, v144
	v_lshlrev_b32_e32 v143, 16, v153
	v_mul_f32_e32 v124, v124, v143
	v_lshlrev_b32_e32 v144, 16, v157
	v_mul_f32_e32 v124, v124, v144
	v_and_b32_e32 v143, 0xffff0000, v153
	v_mul_f32_e32 v125, v125, v143
	v_and_b32_e32 v144, 0xffff0000, v157
	v_mul_f32_e32 v125, v125, v144
	v_cvt_pk_bf16_f32 v150, v126, v127
	v_cvt_pk_bf16_f32 v151, v128, v129
	v_cvt_pk_bf16_f32 v152, v122, v123
	v_cvt_pk_bf16_f32 v153, v124, v125
	global_store_dwordx4 v142, v[150:153], s[16:17]
	s_nop 0
	global_load_dwordx4 v[150:153], v140, s[52:53]
	global_load_dwordx4 v[154:157], v141, s[2:3] offset:2048
	s_waitcnt vmcnt(11)
	v_pk_add_f32 v[118:119], v[118:119], v[232:233]
	v_pk_add_f32 v[120:121], v[120:121], v[234:235]
	v_pk_add_f32 v[114:115], v[114:115], v[236:237]
	v_pk_add_f32 v[116:117], v[116:117], v[238:239]
	v_mul_f32_e32 v118, 0xbfb8aa3b, v118
	v_mul_f32_e32 v119, 0xbfb8aa3b, v119
	v_mul_f32_e32 v120, 0xbfb8aa3b, v120
	v_mul_f32_e32 v121, 0xbfb8aa3b, v121
	v_mul_f32_e32 v114, 0xbfb8aa3b, v114
	v_mul_f32_e32 v115, 0xbfb8aa3b, v115
	v_mul_f32_e32 v116, 0xbfb8aa3b, v116
	v_mul_f32_e32 v117, 0xbfb8aa3b, v117
	v_exp_f32_e32 v118, v118
	v_exp_f32_e32 v119, v119
	v_exp_f32_e32 v120, v120
	v_exp_f32_e32 v121, v121
	v_exp_f32_e32 v114, v114
	v_exp_f32_e32 v115, v115
	v_exp_f32_e32 v116, v116
	v_exp_f32_e32 v117, v117
	v_add_f32_e32 v118, 1.0, v118
	v_add_f32_e32 v119, 1.0, v119
	v_add_f32_e32 v120, 1.0, v120
	v_add_f32_e32 v121, 1.0, v121
	v_add_f32_e32 v114, 1.0, v114
	v_add_f32_e32 v115, 1.0, v115
	v_add_f32_e32 v116, 1.0, v116
	v_add_f32_e32 v117, 1.0, v117
	v_rcp_f32_e32 v118, v118
	v_rcp_f32_e32 v119, v119
	v_rcp_f32_e32 v120, v120
	v_rcp_f32_e32 v121, v121
	v_rcp_f32_e32 v114, v114
	v_rcp_f32_e32 v115, v115
	v_rcp_f32_e32 v116, v116
	v_rcp_f32_e32 v117, v117
	v_lshlrev_b32_e32 v143, 16, v158
	v_mul_f32_e32 v118, v118, v143
	v_lshlrev_b32_e32 v144, 16, v162
	v_mul_f32_e32 v118, v118, v144
	v_and_b32_e32 v143, 0xffff0000, v158
	v_mul_f32_e32 v119, v119, v143
	v_and_b32_e32 v144, 0xffff0000, v162
	v_mul_f32_e32 v119, v119, v144
	v_lshlrev_b32_e32 v143, 16, v159
	v_mul_f32_e32 v120, v120, v143
	v_lshlrev_b32_e32 v144, 16, v163
	v_mul_f32_e32 v120, v120, v144
	v_and_b32_e32 v143, 0xffff0000, v159
	v_mul_f32_e32 v121, v121, v143
	v_and_b32_e32 v144, 0xffff0000, v163
	v_mul_f32_e32 v121, v121, v144
	v_lshlrev_b32_e32 v143, 16, v160
	v_mul_f32_e32 v114, v114, v143
	v_lshlrev_b32_e32 v144, 16, v164
	v_mul_f32_e32 v114, v114, v144
	v_and_b32_e32 v143, 0xffff0000, v160
	v_mul_f32_e32 v115, v115, v143
	v_and_b32_e32 v144, 0xffff0000, v164
	v_mul_f32_e32 v115, v115, v144
	v_lshlrev_b32_e32 v143, 16, v161
	v_mul_f32_e32 v116, v116, v143
	v_lshlrev_b32_e32 v144, 16, v165
	v_mul_f32_e32 v116, v116, v144
	v_and_b32_e32 v143, 0xffff0000, v161
	v_mul_f32_e32 v117, v117, v143
	v_and_b32_e32 v144, 0xffff0000, v165
	v_mul_f32_e32 v117, v117, v144
	v_cvt_pk_bf16_f32 v158, v118, v119
	v_cvt_pk_bf16_f32 v159, v120, v121
	v_cvt_pk_bf16_f32 v160, v114, v115
	v_cvt_pk_bf16_f32 v161, v116, v117
	global_store_dwordx4 v142, v[158:161], s[16:17] offset:256
	v_add_u32_e32 v142, 0x8000, v142
	global_load_dwordx4 v[158:161], v140, s[52:53] offset:256
	global_load_dwordx4 v[162:165], v141, s[2:3] offset:2304
	v_add_u32_e32 v140, 0x28000, v140
	v_add_u32_e32 v141, 0x212000, v141
	s_waitcnt vmcnt(12)
	v_pk_add_f32 v[110:111], v[110:111], v[224:225]
	v_pk_add_f32 v[112:113], v[112:113], v[226:227]
	v_pk_add_f32 v[106:107], v[106:107], v[228:229]
	v_pk_add_f32 v[108:109], v[108:109], v[230:231]
	v_mul_f32_e32 v110, 0xbfb8aa3b, v110
	v_mul_f32_e32 v111, 0xbfb8aa3b, v111
	v_mul_f32_e32 v112, 0xbfb8aa3b, v112
	v_mul_f32_e32 v113, 0xbfb8aa3b, v113
	v_mul_f32_e32 v106, 0xbfb8aa3b, v106
	v_mul_f32_e32 v107, 0xbfb8aa3b, v107
	v_mul_f32_e32 v108, 0xbfb8aa3b, v108
	v_mul_f32_e32 v109, 0xbfb8aa3b, v109
	v_exp_f32_e32 v110, v110
	v_exp_f32_e32 v111, v111
	v_exp_f32_e32 v112, v112
	v_exp_f32_e32 v113, v113
	v_exp_f32_e32 v106, v106
	v_exp_f32_e32 v107, v107
	v_exp_f32_e32 v108, v108
	v_exp_f32_e32 v109, v109
	v_add_f32_e32 v110, 1.0, v110
	v_add_f32_e32 v111, 1.0, v111
	v_add_f32_e32 v112, 1.0, v112
	v_add_f32_e32 v113, 1.0, v113
	v_add_f32_e32 v106, 1.0, v106
	v_add_f32_e32 v107, 1.0, v107
	v_add_f32_e32 v108, 1.0, v108
	v_add_f32_e32 v109, 1.0, v109
	v_rcp_f32_e32 v110, v110
	v_rcp_f32_e32 v111, v111
	v_rcp_f32_e32 v112, v112
	v_rcp_f32_e32 v113, v113
	v_rcp_f32_e32 v106, v106
	v_rcp_f32_e32 v107, v107
	v_rcp_f32_e32 v108, v108
	v_rcp_f32_e32 v109, v109
	v_lshlrev_b32_e32 v143, 16, v166
	v_mul_f32_e32 v110, v110, v143
	v_lshlrev_b32_e32 v144, 16, v170
	v_mul_f32_e32 v110, v110, v144
	v_and_b32_e32 v143, 0xffff0000, v166
	v_mul_f32_e32 v111, v111, v143
	v_and_b32_e32 v144, 0xffff0000, v170
	v_mul_f32_e32 v111, v111, v144
	v_lshlrev_b32_e32 v143, 16, v167
	v_mul_f32_e32 v112, v112, v143
	v_lshlrev_b32_e32 v144, 16, v171
	v_mul_f32_e32 v112, v112, v144
	v_and_b32_e32 v143, 0xffff0000, v167
	v_mul_f32_e32 v113, v113, v143
	v_and_b32_e32 v144, 0xffff0000, v171
	v_mul_f32_e32 v113, v113, v144
	v_lshlrev_b32_e32 v143, 16, v168
	v_mul_f32_e32 v106, v106, v143
	v_lshlrev_b32_e32 v144, 16, v172
	v_mul_f32_e32 v106, v106, v144
	v_and_b32_e32 v143, 0xffff0000, v168
	v_mul_f32_e32 v107, v107, v143
	v_and_b32_e32 v144, 0xffff0000, v172
	v_mul_f32_e32 v107, v107, v144
	v_lshlrev_b32_e32 v143, 16, v169
	v_mul_f32_e32 v108, v108, v143
	v_lshlrev_b32_e32 v144, 16, v173
	v_mul_f32_e32 v108, v108, v144
	v_and_b32_e32 v143, 0xffff0000, v169
	v_mul_f32_e32 v109, v109, v143
	v_and_b32_e32 v144, 0xffff0000, v173
	v_mul_f32_e32 v109, v109, v144
	v_cvt_pk_bf16_f32 v166, v110, v111
	v_cvt_pk_bf16_f32 v167, v112, v113
	v_cvt_pk_bf16_f32 v168, v106, v107
	v_cvt_pk_bf16_f32 v169, v108, v109
	global_store_dwordx4 v142, v[166:169], s[16:17]
	s_nop 0
	global_load_dwordx4 v[166:169], v140, s[52:53]
	global_load_dwordx4 v[170:173], v141, s[2:3] offset:2048
	s_waitcnt vmcnt(13)
	v_pk_add_f32 v[102:103], v[102:103], v[232:233]
	v_pk_add_f32 v[104:105], v[104:105], v[234:235]
	v_pk_add_f32 v[98:99], v[98:99], v[236:237]
	v_pk_add_f32 v[100:101], v[100:101], v[238:239]
	v_mul_f32_e32 v102, 0xbfb8aa3b, v102
	v_mul_f32_e32 v103, 0xbfb8aa3b, v103
	v_mul_f32_e32 v104, 0xbfb8aa3b, v104
	v_mul_f32_e32 v105, 0xbfb8aa3b, v105
	v_mul_f32_e32 v98, 0xbfb8aa3b, v98
	v_mul_f32_e32 v99, 0xbfb8aa3b, v99
	v_mul_f32_e32 v100, 0xbfb8aa3b, v100
	v_mul_f32_e32 v101, 0xbfb8aa3b, v101
	v_exp_f32_e32 v102, v102
	v_exp_f32_e32 v103, v103
	v_exp_f32_e32 v104, v104
	v_exp_f32_e32 v105, v105
	v_exp_f32_e32 v98, v98
	v_exp_f32_e32 v99, v99
	v_exp_f32_e32 v100, v100
	v_exp_f32_e32 v101, v101
	v_add_f32_e32 v102, 1.0, v102
	v_add_f32_e32 v103, 1.0, v103
	v_add_f32_e32 v104, 1.0, v104
	v_add_f32_e32 v105, 1.0, v105
	v_add_f32_e32 v98, 1.0, v98
	v_add_f32_e32 v99, 1.0, v99
	v_add_f32_e32 v100, 1.0, v100
	v_add_f32_e32 v101, 1.0, v101
	v_rcp_f32_e32 v102, v102
	v_rcp_f32_e32 v103, v103
	v_rcp_f32_e32 v104, v104
	v_rcp_f32_e32 v105, v105
	v_rcp_f32_e32 v98, v98
	v_rcp_f32_e32 v99, v99
	v_rcp_f32_e32 v100, v100
	v_rcp_f32_e32 v101, v101
	v_lshlrev_b32_e32 v143, 16, v174
	v_mul_f32_e32 v102, v102, v143
	v_lshlrev_b32_e32 v144, 16, v178
	v_mul_f32_e32 v102, v102, v144
	v_and_b32_e32 v143, 0xffff0000, v174
	v_mul_f32_e32 v103, v103, v143
	v_and_b32_e32 v144, 0xffff0000, v178
	v_mul_f32_e32 v103, v103, v144
	v_lshlrev_b32_e32 v143, 16, v175
	v_mul_f32_e32 v104, v104, v143
	v_lshlrev_b32_e32 v144, 16, v179
	v_mul_f32_e32 v104, v104, v144
	v_and_b32_e32 v143, 0xffff0000, v175
	v_mul_f32_e32 v105, v105, v143
	v_and_b32_e32 v144, 0xffff0000, v179
	v_mul_f32_e32 v105, v105, v144
	v_lshlrev_b32_e32 v143, 16, v176
	v_mul_f32_e32 v98, v98, v143
	v_lshlrev_b32_e32 v144, 16, v180
	v_mul_f32_e32 v98, v98, v144
	v_and_b32_e32 v143, 0xffff0000, v176
	v_mul_f32_e32 v99, v99, v143
	v_and_b32_e32 v144, 0xffff0000, v180
	v_mul_f32_e32 v99, v99, v144
	v_lshlrev_b32_e32 v143, 16, v177
	v_mul_f32_e32 v100, v100, v143
	v_lshlrev_b32_e32 v144, 16, v181
	v_mul_f32_e32 v100, v100, v144
	v_and_b32_e32 v143, 0xffff0000, v177
	v_mul_f32_e32 v101, v101, v143
	v_and_b32_e32 v144, 0xffff0000, v181
	v_mul_f32_e32 v101, v101, v144
	v_cvt_pk_bf16_f32 v174, v102, v103
	v_cvt_pk_bf16_f32 v175, v104, v105
	v_cvt_pk_bf16_f32 v176, v98, v99
	v_cvt_pk_bf16_f32 v177, v100, v101
	global_store_dwordx4 v142, v[174:177], s[16:17] offset:256
	v_add_u32_e32 v142, 0x8000, v142
	global_load_dwordx4 v[174:177], v140, s[52:53] offset:256
	global_load_dwordx4 v[178:181], v141, s[2:3] offset:2304
	v_add_u32_e32 v140, 0x8000, v140
	v_add_u32_e32 v141, 0x6a000, v141
	s_waitcnt vmcnt(14)
	v_pk_add_f32 v[94:95], v[94:95], v[224:225]
	v_pk_add_f32 v[96:97], v[96:97], v[226:227]
	v_pk_add_f32 v[90:91], v[90:91], v[228:229]
	v_pk_add_f32 v[92:93], v[92:93], v[230:231]
	v_mul_f32_e32 v94, 0xbfb8aa3b, v94
	v_mul_f32_e32 v95, 0xbfb8aa3b, v95
	v_mul_f32_e32 v96, 0xbfb8aa3b, v96
	v_mul_f32_e32 v97, 0xbfb8aa3b, v97
	v_mul_f32_e32 v90, 0xbfb8aa3b, v90
	v_mul_f32_e32 v91, 0xbfb8aa3b, v91
	v_mul_f32_e32 v92, 0xbfb8aa3b, v92
	v_mul_f32_e32 v93, 0xbfb8aa3b, v93
	v_exp_f32_e32 v94, v94
	v_exp_f32_e32 v95, v95
	v_exp_f32_e32 v96, v96
	v_exp_f32_e32 v97, v97
	v_exp_f32_e32 v90, v90
	v_exp_f32_e32 v91, v91
	v_exp_f32_e32 v92, v92
	v_exp_f32_e32 v93, v93
	v_add_f32_e32 v94, 1.0, v94
	v_add_f32_e32 v95, 1.0, v95
	v_add_f32_e32 v96, 1.0, v96
	v_add_f32_e32 v97, 1.0, v97
	v_add_f32_e32 v90, 1.0, v90
	v_add_f32_e32 v91, 1.0, v91
	v_add_f32_e32 v92, 1.0, v92
	v_add_f32_e32 v93, 1.0, v93
	v_rcp_f32_e32 v94, v94
	v_rcp_f32_e32 v95, v95
	v_rcp_f32_e32 v96, v96
	v_rcp_f32_e32 v97, v97
	v_rcp_f32_e32 v90, v90
	v_rcp_f32_e32 v91, v91
	v_rcp_f32_e32 v92, v92
	v_rcp_f32_e32 v93, v93
	v_lshlrev_b32_e32 v143, 16, v182
	v_mul_f32_e32 v94, v94, v143
	v_lshlrev_b32_e32 v144, 16, v186
	v_mul_f32_e32 v94, v94, v144
	v_and_b32_e32 v143, 0xffff0000, v182
	v_mul_f32_e32 v95, v95, v143
	v_and_b32_e32 v144, 0xffff0000, v186
	v_mul_f32_e32 v95, v95, v144
	v_lshlrev_b32_e32 v143, 16, v183
	v_mul_f32_e32 v96, v96, v143
	v_lshlrev_b32_e32 v144, 16, v187
	v_mul_f32_e32 v96, v96, v144
	v_and_b32_e32 v143, 0xffff0000, v183
	v_mul_f32_e32 v97, v97, v143
	v_and_b32_e32 v144, 0xffff0000, v187
	v_mul_f32_e32 v97, v97, v144
	v_lshlrev_b32_e32 v143, 16, v184
	v_mul_f32_e32 v90, v90, v143
	v_lshlrev_b32_e32 v144, 16, v188
	v_mul_f32_e32 v90, v90, v144
	v_and_b32_e32 v143, 0xffff0000, v184
	v_mul_f32_e32 v91, v91, v143
	v_and_b32_e32 v144, 0xffff0000, v188
	v_mul_f32_e32 v91, v91, v144
	v_lshlrev_b32_e32 v143, 16, v185
	v_mul_f32_e32 v92, v92, v143
	v_lshlrev_b32_e32 v144, 16, v189
	v_mul_f32_e32 v92, v92, v144
	v_and_b32_e32 v143, 0xffff0000, v185
	v_mul_f32_e32 v93, v93, v143
	v_and_b32_e32 v144, 0xffff0000, v189
	v_mul_f32_e32 v93, v93, v144
	v_cvt_pk_bf16_f32 v182, v94, v95
	v_cvt_pk_bf16_f32 v183, v96, v97
	v_cvt_pk_bf16_f32 v184, v90, v91
	v_cvt_pk_bf16_f32 v185, v92, v93
	global_store_dwordx4 v142, v[182:185], s[16:17]
	s_nop 0
	global_load_dwordx4 v[182:185], v140, s[52:53]
	global_load_dwordx4 v[186:189], v141, s[2:3] offset:2048
	s_waitcnt vmcnt(15)
	v_pk_add_f32 v[86:87], v[86:87], v[232:233]
	v_pk_add_f32 v[88:89], v[88:89], v[234:235]
	v_pk_add_f32 v[82:83], v[82:83], v[236:237]
	v_pk_add_f32 v[84:85], v[84:85], v[238:239]
	v_mul_f32_e32 v86, 0xbfb8aa3b, v86
	v_mul_f32_e32 v87, 0xbfb8aa3b, v87
	v_mul_f32_e32 v88, 0xbfb8aa3b, v88
	v_mul_f32_e32 v89, 0xbfb8aa3b, v89
	v_mul_f32_e32 v82, 0xbfb8aa3b, v82
	v_mul_f32_e32 v83, 0xbfb8aa3b, v83
	v_mul_f32_e32 v84, 0xbfb8aa3b, v84
	v_mul_f32_e32 v85, 0xbfb8aa3b, v85
	v_exp_f32_e32 v86, v86
	v_exp_f32_e32 v87, v87
	v_exp_f32_e32 v88, v88
	v_exp_f32_e32 v89, v89
	v_exp_f32_e32 v82, v82
	v_exp_f32_e32 v83, v83
	v_exp_f32_e32 v84, v84
	v_exp_f32_e32 v85, v85
	v_add_f32_e32 v86, 1.0, v86
	v_add_f32_e32 v87, 1.0, v87
	v_add_f32_e32 v88, 1.0, v88
	v_add_f32_e32 v89, 1.0, v89
	v_add_f32_e32 v82, 1.0, v82
	v_add_f32_e32 v83, 1.0, v83
	v_add_f32_e32 v84, 1.0, v84
	v_add_f32_e32 v85, 1.0, v85
	v_rcp_f32_e32 v86, v86
	v_rcp_f32_e32 v87, v87
	v_rcp_f32_e32 v88, v88
	v_rcp_f32_e32 v89, v89
	v_rcp_f32_e32 v82, v82
	v_rcp_f32_e32 v83, v83
	v_rcp_f32_e32 v84, v84
	v_rcp_f32_e32 v85, v85
	v_lshlrev_b32_e32 v143, 16, v190
	v_mul_f32_e32 v86, v86, v143
	v_lshlrev_b32_e32 v144, 16, v194
	v_mul_f32_e32 v86, v86, v144
	v_and_b32_e32 v143, 0xffff0000, v190
	v_mul_f32_e32 v87, v87, v143
	v_and_b32_e32 v144, 0xffff0000, v194
	v_mul_f32_e32 v87, v87, v144
	v_lshlrev_b32_e32 v143, 16, v191
	v_mul_f32_e32 v88, v88, v143
	v_lshlrev_b32_e32 v144, 16, v195
	v_mul_f32_e32 v88, v88, v144
	v_and_b32_e32 v143, 0xffff0000, v191
	v_mul_f32_e32 v89, v89, v143
	v_and_b32_e32 v144, 0xffff0000, v195
	v_mul_f32_e32 v89, v89, v144
	v_lshlrev_b32_e32 v143, 16, v192
	v_mul_f32_e32 v82, v82, v143
	v_lshlrev_b32_e32 v144, 16, v196
	v_mul_f32_e32 v82, v82, v144
	v_and_b32_e32 v143, 0xffff0000, v192
	v_mul_f32_e32 v83, v83, v143
	v_and_b32_e32 v144, 0xffff0000, v196
	v_mul_f32_e32 v83, v83, v144
	v_lshlrev_b32_e32 v143, 16, v193
	v_mul_f32_e32 v84, v84, v143
	v_lshlrev_b32_e32 v144, 16, v197
	v_mul_f32_e32 v84, v84, v144
	v_and_b32_e32 v143, 0xffff0000, v193
	v_mul_f32_e32 v85, v85, v143
	v_and_b32_e32 v144, 0xffff0000, v197
	v_mul_f32_e32 v85, v85, v144
	v_cvt_pk_bf16_f32 v190, v86, v87
	v_cvt_pk_bf16_f32 v191, v88, v89
	v_cvt_pk_bf16_f32 v192, v82, v83
	v_cvt_pk_bf16_f32 v193, v84, v85
	global_store_dwordx4 v142, v[190:193], s[16:17] offset:256
	v_add_u32_e32 v142, 0x8000, v142
	global_load_dwordx4 v[190:193], v140, s[52:53] offset:256
	global_load_dwordx4 v[194:197], v141, s[2:3] offset:2304
	v_add_u32_e32 v140, 0x8000, v140
	v_add_u32_e32 v141, 0x6a000, v141
	s_waitcnt vmcnt(15)
	v_pk_add_f32 v[78:79], v[78:79], v[224:225]
	v_pk_add_f32 v[80:81], v[80:81], v[226:227]
	v_pk_add_f32 v[74:75], v[74:75], v[228:229]
	v_pk_add_f32 v[76:77], v[76:77], v[230:231]
	v_mul_f32_e32 v78, 0xbfb8aa3b, v78
	v_mul_f32_e32 v79, 0xbfb8aa3b, v79
	v_mul_f32_e32 v80, 0xbfb8aa3b, v80
	v_mul_f32_e32 v81, 0xbfb8aa3b, v81
	v_mul_f32_e32 v74, 0xbfb8aa3b, v74
	v_mul_f32_e32 v75, 0xbfb8aa3b, v75
	v_mul_f32_e32 v76, 0xbfb8aa3b, v76
	v_mul_f32_e32 v77, 0xbfb8aa3b, v77
	v_exp_f32_e32 v78, v78
	v_exp_f32_e32 v79, v79
	v_exp_f32_e32 v80, v80
	v_exp_f32_e32 v81, v81
	v_exp_f32_e32 v74, v74
	v_exp_f32_e32 v75, v75
	v_exp_f32_e32 v76, v76
	v_exp_f32_e32 v77, v77
	v_add_f32_e32 v78, 1.0, v78
	v_add_f32_e32 v79, 1.0, v79
	v_add_f32_e32 v80, 1.0, v80
	v_add_f32_e32 v81, 1.0, v81
	v_add_f32_e32 v74, 1.0, v74
	v_add_f32_e32 v75, 1.0, v75
	v_add_f32_e32 v76, 1.0, v76
	v_add_f32_e32 v77, 1.0, v77
	v_rcp_f32_e32 v78, v78
	v_rcp_f32_e32 v79, v79
	v_rcp_f32_e32 v80, v80
	v_rcp_f32_e32 v81, v81
	v_rcp_f32_e32 v74, v74
	v_rcp_f32_e32 v75, v75
	v_rcp_f32_e32 v76, v76
	v_rcp_f32_e32 v77, v77
	v_lshlrev_b32_e32 v143, 16, v150
	v_mul_f32_e32 v78, v78, v143
	v_lshlrev_b32_e32 v144, 16, v154
	v_mul_f32_e32 v78, v78, v144
	v_and_b32_e32 v143, 0xffff0000, v150
	v_mul_f32_e32 v79, v79, v143
	v_and_b32_e32 v144, 0xffff0000, v154
	v_mul_f32_e32 v79, v79, v144
	v_lshlrev_b32_e32 v143, 16, v151
	v_mul_f32_e32 v80, v80, v143
	v_lshlrev_b32_e32 v144, 16, v155
	v_mul_f32_e32 v80, v80, v144
	v_and_b32_e32 v143, 0xffff0000, v151
	v_mul_f32_e32 v81, v81, v143
	v_and_b32_e32 v144, 0xffff0000, v155
	v_mul_f32_e32 v81, v81, v144
	v_lshlrev_b32_e32 v143, 16, v152
	v_mul_f32_e32 v74, v74, v143
	v_lshlrev_b32_e32 v144, 16, v156
	v_mul_f32_e32 v74, v74, v144
	v_and_b32_e32 v143, 0xffff0000, v152
	v_mul_f32_e32 v75, v75, v143
	v_and_b32_e32 v144, 0xffff0000, v156
	v_mul_f32_e32 v75, v75, v144
	v_lshlrev_b32_e32 v143, 16, v153
	v_mul_f32_e32 v76, v76, v143
	v_lshlrev_b32_e32 v144, 16, v157
	v_mul_f32_e32 v76, v76, v144
	v_and_b32_e32 v143, 0xffff0000, v153
	v_mul_f32_e32 v77, v77, v143
	v_and_b32_e32 v144, 0xffff0000, v157
	v_mul_f32_e32 v77, v77, v144
	v_cvt_pk_bf16_f32 v150, v78, v79
	v_cvt_pk_bf16_f32 v151, v80, v81
	v_cvt_pk_bf16_f32 v152, v74, v75
	v_cvt_pk_bf16_f32 v153, v76, v77
	global_store_dwordx4 v142, v[150:153], s[16:17]
	s_nop 0
	global_load_dwordx4 v[150:153], v140, s[52:53]
	global_load_dwordx4 v[154:157], v141, s[2:3] offset:2048
	s_waitcnt vmcnt(15)
	v_pk_add_f32 v[70:71], v[70:71], v[232:233]
	v_pk_add_f32 v[72:73], v[72:73], v[234:235]
	v_pk_add_f32 v[66:67], v[66:67], v[236:237]
	v_pk_add_f32 v[68:69], v[68:69], v[238:239]
	v_mul_f32_e32 v70, 0xbfb8aa3b, v70
	v_mul_f32_e32 v71, 0xbfb8aa3b, v71
	v_mul_f32_e32 v72, 0xbfb8aa3b, v72
	v_mul_f32_e32 v73, 0xbfb8aa3b, v73
	v_mul_f32_e32 v66, 0xbfb8aa3b, v66
	v_mul_f32_e32 v67, 0xbfb8aa3b, v67
	v_mul_f32_e32 v68, 0xbfb8aa3b, v68
	v_mul_f32_e32 v69, 0xbfb8aa3b, v69
	v_exp_f32_e32 v70, v70
	v_exp_f32_e32 v71, v71
	v_exp_f32_e32 v72, v72
	v_exp_f32_e32 v73, v73
	v_exp_f32_e32 v66, v66
	v_exp_f32_e32 v67, v67
	v_exp_f32_e32 v68, v68
	v_exp_f32_e32 v69, v69
	v_add_f32_e32 v70, 1.0, v70
	v_add_f32_e32 v71, 1.0, v71
	v_add_f32_e32 v72, 1.0, v72
	v_add_f32_e32 v73, 1.0, v73
	v_add_f32_e32 v66, 1.0, v66
	v_add_f32_e32 v67, 1.0, v67
	v_add_f32_e32 v68, 1.0, v68
	v_add_f32_e32 v69, 1.0, v69
	v_rcp_f32_e32 v70, v70
	v_rcp_f32_e32 v71, v71
	v_rcp_f32_e32 v72, v72
	v_rcp_f32_e32 v73, v73
	v_rcp_f32_e32 v66, v66
	v_rcp_f32_e32 v67, v67
	v_rcp_f32_e32 v68, v68
	v_rcp_f32_e32 v69, v69
	v_lshlrev_b32_e32 v143, 16, v158
	v_mul_f32_e32 v70, v70, v143
	v_lshlrev_b32_e32 v144, 16, v162
	v_mul_f32_e32 v70, v70, v144
	v_and_b32_e32 v143, 0xffff0000, v158
	v_mul_f32_e32 v71, v71, v143
	v_and_b32_e32 v144, 0xffff0000, v162
	v_mul_f32_e32 v71, v71, v144
	v_lshlrev_b32_e32 v143, 16, v159
	v_mul_f32_e32 v72, v72, v143
	v_lshlrev_b32_e32 v144, 16, v163
	v_mul_f32_e32 v72, v72, v144
	v_and_b32_e32 v143, 0xffff0000, v159
	v_mul_f32_e32 v73, v73, v143
	v_and_b32_e32 v144, 0xffff0000, v163
	v_mul_f32_e32 v73, v73, v144
	v_lshlrev_b32_e32 v143, 16, v160
	v_mul_f32_e32 v66, v66, v143
	v_lshlrev_b32_e32 v144, 16, v164
	v_mul_f32_e32 v66, v66, v144
	v_and_b32_e32 v143, 0xffff0000, v160
	v_mul_f32_e32 v67, v67, v143
	v_and_b32_e32 v144, 0xffff0000, v164
	v_mul_f32_e32 v67, v67, v144
	v_lshlrev_b32_e32 v143, 16, v161
	v_mul_f32_e32 v68, v68, v143
	v_lshlrev_b32_e32 v144, 16, v165
	v_mul_f32_e32 v68, v68, v144
	v_and_b32_e32 v143, 0xffff0000, v161
	v_mul_f32_e32 v69, v69, v143
	v_and_b32_e32 v144, 0xffff0000, v165
	v_mul_f32_e32 v69, v69, v144
	v_cvt_pk_bf16_f32 v158, v70, v71
	v_cvt_pk_bf16_f32 v159, v72, v73
	v_cvt_pk_bf16_f32 v160, v66, v67
	v_cvt_pk_bf16_f32 v161, v68, v69
	global_store_dwordx4 v142, v[158:161], s[16:17] offset:256
	v_add_u32_e32 v142, 0x28000, v142
	global_load_dwordx4 v[158:161], v140, s[52:53] offset:256
	global_load_dwordx4 v[162:165], v141, s[2:3] offset:2304
	v_add_u32_e32 v140, 0x8000, v140
	v_add_u32_e32 v141, 0x6a000, v141
	s_waitcnt vmcnt(15)
	v_pk_add_f32 v[62:63], v[62:63], v[224:225]
	v_pk_add_f32 v[64:65], v[64:65], v[226:227]
	v_pk_add_f32 v[58:59], v[58:59], v[228:229]
	v_pk_add_f32 v[60:61], v[60:61], v[230:231]
	v_mul_f32_e32 v62, 0xbfb8aa3b, v62
	v_mul_f32_e32 v63, 0xbfb8aa3b, v63
	v_mul_f32_e32 v64, 0xbfb8aa3b, v64
	v_mul_f32_e32 v65, 0xbfb8aa3b, v65
	v_mul_f32_e32 v58, 0xbfb8aa3b, v58
	v_mul_f32_e32 v59, 0xbfb8aa3b, v59
	v_mul_f32_e32 v60, 0xbfb8aa3b, v60
	v_mul_f32_e32 v61, 0xbfb8aa3b, v61
	v_exp_f32_e32 v62, v62
	v_exp_f32_e32 v63, v63
	v_exp_f32_e32 v64, v64
	v_exp_f32_e32 v65, v65
	v_exp_f32_e32 v58, v58
	v_exp_f32_e32 v59, v59
	v_exp_f32_e32 v60, v60
	v_exp_f32_e32 v61, v61
	v_add_f32_e32 v62, 1.0, v62
	v_add_f32_e32 v63, 1.0, v63
	v_add_f32_e32 v64, 1.0, v64
	v_add_f32_e32 v65, 1.0, v65
	v_add_f32_e32 v58, 1.0, v58
	v_add_f32_e32 v59, 1.0, v59
	v_add_f32_e32 v60, 1.0, v60
	v_add_f32_e32 v61, 1.0, v61
	v_rcp_f32_e32 v62, v62
	v_rcp_f32_e32 v63, v63
	v_rcp_f32_e32 v64, v64
	v_rcp_f32_e32 v65, v65
	v_rcp_f32_e32 v58, v58
	v_rcp_f32_e32 v59, v59
	v_rcp_f32_e32 v60, v60
	v_rcp_f32_e32 v61, v61
	v_lshlrev_b32_e32 v143, 16, v166
	v_mul_f32_e32 v62, v62, v143
	v_lshlrev_b32_e32 v144, 16, v170
	v_mul_f32_e32 v62, v62, v144
	v_and_b32_e32 v143, 0xffff0000, v166
	v_mul_f32_e32 v63, v63, v143
	v_and_b32_e32 v144, 0xffff0000, v170
	v_mul_f32_e32 v63, v63, v144
	v_lshlrev_b32_e32 v143, 16, v167
	v_mul_f32_e32 v64, v64, v143
	v_lshlrev_b32_e32 v144, 16, v171
	v_mul_f32_e32 v64, v64, v144
	v_and_b32_e32 v143, 0xffff0000, v167
	v_mul_f32_e32 v65, v65, v143
	v_and_b32_e32 v144, 0xffff0000, v171
	v_mul_f32_e32 v65, v65, v144
	v_lshlrev_b32_e32 v143, 16, v168
	v_mul_f32_e32 v58, v58, v143
	v_lshlrev_b32_e32 v144, 16, v172
	v_mul_f32_e32 v58, v58, v144
	v_and_b32_e32 v143, 0xffff0000, v168
	v_mul_f32_e32 v59, v59, v143
	v_and_b32_e32 v144, 0xffff0000, v172
	v_mul_f32_e32 v59, v59, v144
	v_lshlrev_b32_e32 v143, 16, v169
	v_mul_f32_e32 v60, v60, v143
	v_lshlrev_b32_e32 v144, 16, v173
	v_mul_f32_e32 v60, v60, v144
	v_and_b32_e32 v143, 0xffff0000, v169
	v_mul_f32_e32 v61, v61, v143
	v_and_b32_e32 v144, 0xffff0000, v173
	v_mul_f32_e32 v61, v61, v144
	v_cvt_pk_bf16_f32 v166, v62, v63
	v_cvt_pk_bf16_f32 v167, v64, v65
	v_cvt_pk_bf16_f32 v168, v58, v59
	v_cvt_pk_bf16_f32 v169, v60, v61
	global_store_dwordx4 v142, v[166:169], s[16:17]
	s_nop 0
	global_load_dwordx4 v[166:169], v140, s[52:53]
	global_load_dwordx4 v[170:173], v141, s[2:3] offset:2048
	s_waitcnt vmcnt(15)
	v_pk_add_f32 v[54:55], v[54:55], v[232:233]
	v_pk_add_f32 v[56:57], v[56:57], v[234:235]
	v_pk_add_f32 v[50:51], v[50:51], v[236:237]
	v_pk_add_f32 v[52:53], v[52:53], v[238:239]
	v_mul_f32_e32 v54, 0xbfb8aa3b, v54
	v_mul_f32_e32 v55, 0xbfb8aa3b, v55
	v_mul_f32_e32 v56, 0xbfb8aa3b, v56
	v_mul_f32_e32 v57, 0xbfb8aa3b, v57
	v_mul_f32_e32 v50, 0xbfb8aa3b, v50
	v_mul_f32_e32 v51, 0xbfb8aa3b, v51
	v_mul_f32_e32 v52, 0xbfb8aa3b, v52
	v_mul_f32_e32 v53, 0xbfb8aa3b, v53
	v_exp_f32_e32 v54, v54
	v_exp_f32_e32 v55, v55
	v_exp_f32_e32 v56, v56
	v_exp_f32_e32 v57, v57
	v_exp_f32_e32 v50, v50
	v_exp_f32_e32 v51, v51
	v_exp_f32_e32 v52, v52
	v_exp_f32_e32 v53, v53
	v_add_f32_e32 v54, 1.0, v54
	v_add_f32_e32 v55, 1.0, v55
	v_add_f32_e32 v56, 1.0, v56
	v_add_f32_e32 v57, 1.0, v57
	v_add_f32_e32 v50, 1.0, v50
	v_add_f32_e32 v51, 1.0, v51
	v_add_f32_e32 v52, 1.0, v52
	v_add_f32_e32 v53, 1.0, v53
	v_rcp_f32_e32 v54, v54
	v_rcp_f32_e32 v55, v55
	v_rcp_f32_e32 v56, v56
	v_rcp_f32_e32 v57, v57
	v_rcp_f32_e32 v50, v50
	v_rcp_f32_e32 v51, v51
	v_rcp_f32_e32 v52, v52
	v_rcp_f32_e32 v53, v53
	v_lshlrev_b32_e32 v143, 16, v174
	v_mul_f32_e32 v54, v54, v143
	v_lshlrev_b32_e32 v144, 16, v178
	v_mul_f32_e32 v54, v54, v144
	v_and_b32_e32 v143, 0xffff0000, v174
	v_mul_f32_e32 v55, v55, v143
	v_and_b32_e32 v144, 0xffff0000, v178
	v_mul_f32_e32 v55, v55, v144
	v_lshlrev_b32_e32 v143, 16, v175
	v_mul_f32_e32 v56, v56, v143
	v_lshlrev_b32_e32 v144, 16, v179
	v_mul_f32_e32 v56, v56, v144
	v_and_b32_e32 v143, 0xffff0000, v175
	v_mul_f32_e32 v57, v57, v143
	v_and_b32_e32 v144, 0xffff0000, v179
	v_mul_f32_e32 v57, v57, v144
	v_lshlrev_b32_e32 v143, 16, v176
	v_mul_f32_e32 v50, v50, v143
	v_lshlrev_b32_e32 v144, 16, v180
	v_mul_f32_e32 v50, v50, v144
	v_and_b32_e32 v143, 0xffff0000, v176
	v_mul_f32_e32 v51, v51, v143
	v_and_b32_e32 v144, 0xffff0000, v180
	v_mul_f32_e32 v51, v51, v144
	v_lshlrev_b32_e32 v143, 16, v177
	v_mul_f32_e32 v52, v52, v143
	v_lshlrev_b32_e32 v144, 16, v181
	v_mul_f32_e32 v52, v52, v144
	v_and_b32_e32 v143, 0xffff0000, v177
	v_mul_f32_e32 v53, v53, v143
	v_and_b32_e32 v144, 0xffff0000, v181
	v_mul_f32_e32 v53, v53, v144
	v_cvt_pk_bf16_f32 v174, v54, v55
	v_cvt_pk_bf16_f32 v175, v56, v57
	v_cvt_pk_bf16_f32 v176, v50, v51
	v_cvt_pk_bf16_f32 v177, v52, v53
	global_store_dwordx4 v142, v[174:177], s[16:17] offset:256
	v_add_u32_e32 v142, 0x8000, v142
	global_load_dwordx4 v[174:177], v140, s[52:53] offset:256
	global_load_dwordx4 v[178:181], v141, s[2:3] offset:2304
	s_waitcnt vmcnt(15)
	v_pk_add_f32 v[46:47], v[46:47], v[224:225]
	v_pk_add_f32 v[48:49], v[48:49], v[226:227]
	v_pk_add_f32 v[42:43], v[42:43], v[228:229]
	v_pk_add_f32 v[44:45], v[44:45], v[230:231]
	v_mul_f32_e32 v46, 0xbfb8aa3b, v46
	v_mul_f32_e32 v47, 0xbfb8aa3b, v47
	v_mul_f32_e32 v48, 0xbfb8aa3b, v48
	v_mul_f32_e32 v49, 0xbfb8aa3b, v49
	v_mul_f32_e32 v42, 0xbfb8aa3b, v42
	v_mul_f32_e32 v43, 0xbfb8aa3b, v43
	v_mul_f32_e32 v44, 0xbfb8aa3b, v44
	v_mul_f32_e32 v45, 0xbfb8aa3b, v45
	v_exp_f32_e32 v46, v46
	v_exp_f32_e32 v47, v47
	v_exp_f32_e32 v48, v48
	v_exp_f32_e32 v49, v49
	v_exp_f32_e32 v42, v42
	v_exp_f32_e32 v43, v43
	v_exp_f32_e32 v44, v44
	v_exp_f32_e32 v45, v45
	v_add_f32_e32 v46, 1.0, v46
	v_add_f32_e32 v47, 1.0, v47
	v_add_f32_e32 v48, 1.0, v48
	v_add_f32_e32 v49, 1.0, v49
	v_add_f32_e32 v42, 1.0, v42
	v_add_f32_e32 v43, 1.0, v43
	v_add_f32_e32 v44, 1.0, v44
	v_add_f32_e32 v45, 1.0, v45
	v_rcp_f32_e32 v46, v46
	v_rcp_f32_e32 v47, v47
	v_rcp_f32_e32 v48, v48
	v_rcp_f32_e32 v49, v49
	v_rcp_f32_e32 v42, v42
	v_rcp_f32_e32 v43, v43
	v_rcp_f32_e32 v44, v44
	v_rcp_f32_e32 v45, v45
	v_lshlrev_b32_e32 v143, 16, v182
	v_mul_f32_e32 v46, v46, v143
	v_lshlrev_b32_e32 v144, 16, v186
	v_mul_f32_e32 v46, v46, v144
	v_and_b32_e32 v143, 0xffff0000, v182
	v_mul_f32_e32 v47, v47, v143
	v_and_b32_e32 v144, 0xffff0000, v186
	v_mul_f32_e32 v47, v47, v144
	v_lshlrev_b32_e32 v143, 16, v183
	v_mul_f32_e32 v48, v48, v143
	v_lshlrev_b32_e32 v144, 16, v187
	v_mul_f32_e32 v48, v48, v144
	v_and_b32_e32 v143, 0xffff0000, v183
	v_mul_f32_e32 v49, v49, v143
	v_and_b32_e32 v144, 0xffff0000, v187
	v_mul_f32_e32 v49, v49, v144
	v_lshlrev_b32_e32 v143, 16, v184
	v_mul_f32_e32 v42, v42, v143
	v_lshlrev_b32_e32 v144, 16, v188
	v_mul_f32_e32 v42, v42, v144
	v_and_b32_e32 v143, 0xffff0000, v184
	v_mul_f32_e32 v43, v43, v143
	v_and_b32_e32 v144, 0xffff0000, v188
	v_mul_f32_e32 v43, v43, v144
	v_lshlrev_b32_e32 v143, 16, v185
	v_mul_f32_e32 v44, v44, v143
	v_lshlrev_b32_e32 v144, 16, v189
	v_mul_f32_e32 v44, v44, v144
	v_and_b32_e32 v143, 0xffff0000, v185
	v_mul_f32_e32 v45, v45, v143
	v_and_b32_e32 v144, 0xffff0000, v189
	v_mul_f32_e32 v45, v45, v144
	v_cvt_pk_bf16_f32 v182, v46, v47
	v_cvt_pk_bf16_f32 v183, v48, v49
	v_cvt_pk_bf16_f32 v184, v42, v43
	v_cvt_pk_bf16_f32 v185, v44, v45
	global_store_dwordx4 v142, v[182:185], s[16:17]
	s_nop 0
	s_waitcnt vmcnt(13)
	v_pk_add_f32 v[38:39], v[38:39], v[232:233]
	v_pk_add_f32 v[40:41], v[40:41], v[234:235]
	v_pk_add_f32 v[34:35], v[34:35], v[236:237]
	v_pk_add_f32 v[36:37], v[36:37], v[238:239]
	v_mul_f32_e32 v38, 0xbfb8aa3b, v38
	v_mul_f32_e32 v39, 0xbfb8aa3b, v39
	v_mul_f32_e32 v40, 0xbfb8aa3b, v40
	v_mul_f32_e32 v41, 0xbfb8aa3b, v41
	v_mul_f32_e32 v34, 0xbfb8aa3b, v34
	v_mul_f32_e32 v35, 0xbfb8aa3b, v35
	v_mul_f32_e32 v36, 0xbfb8aa3b, v36
	v_mul_f32_e32 v37, 0xbfb8aa3b, v37
	v_exp_f32_e32 v38, v38
	v_exp_f32_e32 v39, v39
	v_exp_f32_e32 v40, v40
	v_exp_f32_e32 v41, v41
	v_exp_f32_e32 v34, v34
	v_exp_f32_e32 v35, v35
	v_exp_f32_e32 v36, v36
	v_exp_f32_e32 v37, v37
	v_add_f32_e32 v38, 1.0, v38
	v_add_f32_e32 v39, 1.0, v39
	v_add_f32_e32 v40, 1.0, v40
	v_add_f32_e32 v41, 1.0, v41
	v_add_f32_e32 v34, 1.0, v34
	v_add_f32_e32 v35, 1.0, v35
	v_add_f32_e32 v36, 1.0, v36
	v_add_f32_e32 v37, 1.0, v37
	v_rcp_f32_e32 v38, v38
	v_rcp_f32_e32 v39, v39
	v_rcp_f32_e32 v40, v40
	v_rcp_f32_e32 v41, v41
	v_rcp_f32_e32 v34, v34
	v_rcp_f32_e32 v35, v35
	v_rcp_f32_e32 v36, v36
	v_rcp_f32_e32 v37, v37
	v_lshlrev_b32_e32 v143, 16, v190
	v_mul_f32_e32 v38, v38, v143
	v_lshlrev_b32_e32 v144, 16, v194
	v_mul_f32_e32 v38, v38, v144
	v_and_b32_e32 v143, 0xffff0000, v190
	v_mul_f32_e32 v39, v39, v143
	v_and_b32_e32 v144, 0xffff0000, v194
	v_mul_f32_e32 v39, v39, v144
	v_lshlrev_b32_e32 v143, 16, v191
	v_mul_f32_e32 v40, v40, v143
	v_lshlrev_b32_e32 v144, 16, v195
	v_mul_f32_e32 v40, v40, v144
	v_and_b32_e32 v143, 0xffff0000, v191
	v_mul_f32_e32 v41, v41, v143
	v_and_b32_e32 v144, 0xffff0000, v195
	v_mul_f32_e32 v41, v41, v144
	v_lshlrev_b32_e32 v143, 16, v192
	v_mul_f32_e32 v34, v34, v143
	v_lshlrev_b32_e32 v144, 16, v196
	v_mul_f32_e32 v34, v34, v144
	v_and_b32_e32 v143, 0xffff0000, v192
	v_mul_f32_e32 v35, v35, v143
	v_and_b32_e32 v144, 0xffff0000, v196
	v_mul_f32_e32 v35, v35, v144
	v_lshlrev_b32_e32 v143, 16, v193
	v_mul_f32_e32 v36, v36, v143
	v_lshlrev_b32_e32 v144, 16, v197
	v_mul_f32_e32 v36, v36, v144
	v_and_b32_e32 v143, 0xffff0000, v193
	v_mul_f32_e32 v37, v37, v143
	v_and_b32_e32 v144, 0xffff0000, v197
	v_mul_f32_e32 v37, v37, v144
	v_cvt_pk_bf16_f32 v190, v38, v39
	v_cvt_pk_bf16_f32 v191, v40, v41
	v_cvt_pk_bf16_f32 v192, v34, v35
	v_cvt_pk_bf16_f32 v193, v36, v37
	global_store_dwordx4 v142, v[190:193], s[16:17] offset:256
	v_add_u32_e32 v142, 0x8000, v142
	s_waitcnt vmcnt(11)
	v_pk_add_f32 v[30:31], v[30:31], v[224:225]
	v_pk_add_f32 v[32:33], v[32:33], v[226:227]
	v_pk_add_f32 v[26:27], v[26:27], v[228:229]
	v_pk_add_f32 v[28:29], v[28:29], v[230:231]
	v_mul_f32_e32 v30, 0xbfb8aa3b, v30
	v_mul_f32_e32 v31, 0xbfb8aa3b, v31
	v_mul_f32_e32 v32, 0xbfb8aa3b, v32
	v_mul_f32_e32 v33, 0xbfb8aa3b, v33
	v_mul_f32_e32 v26, 0xbfb8aa3b, v26
	v_mul_f32_e32 v27, 0xbfb8aa3b, v27
	v_mul_f32_e32 v28, 0xbfb8aa3b, v28
	v_mul_f32_e32 v29, 0xbfb8aa3b, v29
	v_exp_f32_e32 v30, v30
	v_exp_f32_e32 v31, v31
	v_exp_f32_e32 v32, v32
	v_exp_f32_e32 v33, v33
	v_exp_f32_e32 v26, v26
	v_exp_f32_e32 v27, v27
	v_exp_f32_e32 v28, v28
	v_exp_f32_e32 v29, v29
	v_add_f32_e32 v30, 1.0, v30
	v_add_f32_e32 v31, 1.0, v31
	v_add_f32_e32 v32, 1.0, v32
	v_add_f32_e32 v33, 1.0, v33
	v_add_f32_e32 v26, 1.0, v26
	v_add_f32_e32 v27, 1.0, v27
	v_add_f32_e32 v28, 1.0, v28
	v_add_f32_e32 v29, 1.0, v29
	v_rcp_f32_e32 v30, v30
	v_rcp_f32_e32 v31, v31
	v_rcp_f32_e32 v32, v32
	v_rcp_f32_e32 v33, v33
	v_rcp_f32_e32 v26, v26
	v_rcp_f32_e32 v27, v27
	v_rcp_f32_e32 v28, v28
	v_rcp_f32_e32 v29, v29
	v_lshlrev_b32_e32 v143, 16, v150
	v_mul_f32_e32 v30, v30, v143
	v_lshlrev_b32_e32 v144, 16, v154
	v_mul_f32_e32 v30, v30, v144
	v_and_b32_e32 v143, 0xffff0000, v150
	v_mul_f32_e32 v31, v31, v143
	v_and_b32_e32 v144, 0xffff0000, v154
	v_mul_f32_e32 v31, v31, v144
	v_lshlrev_b32_e32 v143, 16, v151
	v_mul_f32_e32 v32, v32, v143
	v_lshlrev_b32_e32 v144, 16, v155
	v_mul_f32_e32 v32, v32, v144
	v_and_b32_e32 v143, 0xffff0000, v151
	v_mul_f32_e32 v33, v33, v143
	v_and_b32_e32 v144, 0xffff0000, v155
	v_mul_f32_e32 v33, v33, v144
	v_lshlrev_b32_e32 v143, 16, v152
	v_mul_f32_e32 v26, v26, v143
	v_lshlrev_b32_e32 v144, 16, v156
	v_mul_f32_e32 v26, v26, v144
	v_and_b32_e32 v143, 0xffff0000, v152
	v_mul_f32_e32 v27, v27, v143
	v_and_b32_e32 v144, 0xffff0000, v156
	v_mul_f32_e32 v27, v27, v144
	v_lshlrev_b32_e32 v143, 16, v153
	v_mul_f32_e32 v28, v28, v143
	v_lshlrev_b32_e32 v144, 16, v157
	v_mul_f32_e32 v28, v28, v144
	v_and_b32_e32 v143, 0xffff0000, v153
	v_mul_f32_e32 v29, v29, v143
	v_and_b32_e32 v144, 0xffff0000, v157
	v_mul_f32_e32 v29, v29, v144
	v_cvt_pk_bf16_f32 v150, v30, v31
	v_cvt_pk_bf16_f32 v151, v32, v33
	v_cvt_pk_bf16_f32 v152, v26, v27
	v_cvt_pk_bf16_f32 v153, v28, v29
	global_store_dwordx4 v142, v[150:153], s[16:17]
	s_nop 0
	s_waitcnt vmcnt(9)
	v_pk_add_f32 v[22:23], v[22:23], v[232:233]
	v_pk_add_f32 v[24:25], v[24:25], v[234:235]
	v_pk_add_f32 v[18:19], v[18:19], v[236:237]
	v_pk_add_f32 v[20:21], v[20:21], v[238:239]
	v_mul_f32_e32 v22, 0xbfb8aa3b, v22
	v_mul_f32_e32 v23, 0xbfb8aa3b, v23
	v_mul_f32_e32 v24, 0xbfb8aa3b, v24
	v_mul_f32_e32 v25, 0xbfb8aa3b, v25
	v_mul_f32_e32 v18, 0xbfb8aa3b, v18
	v_mul_f32_e32 v19, 0xbfb8aa3b, v19
	v_mul_f32_e32 v20, 0xbfb8aa3b, v20
	v_mul_f32_e32 v21, 0xbfb8aa3b, v21
	v_exp_f32_e32 v22, v22
	v_exp_f32_e32 v23, v23
	v_exp_f32_e32 v24, v24
	v_exp_f32_e32 v25, v25
	v_exp_f32_e32 v18, v18
	v_exp_f32_e32 v19, v19
	v_exp_f32_e32 v20, v20
	v_exp_f32_e32 v21, v21
	v_add_f32_e32 v22, 1.0, v22
	v_add_f32_e32 v23, 1.0, v23
	v_add_f32_e32 v24, 1.0, v24
	v_add_f32_e32 v25, 1.0, v25
	v_add_f32_e32 v18, 1.0, v18
	v_add_f32_e32 v19, 1.0, v19
	v_add_f32_e32 v20, 1.0, v20
	v_add_f32_e32 v21, 1.0, v21
	v_rcp_f32_e32 v22, v22
	v_rcp_f32_e32 v23, v23
	v_rcp_f32_e32 v24, v24
	v_rcp_f32_e32 v25, v25
	v_rcp_f32_e32 v18, v18
	v_rcp_f32_e32 v19, v19
	v_rcp_f32_e32 v20, v20
	v_rcp_f32_e32 v21, v21
	v_lshlrev_b32_e32 v143, 16, v158
	v_mul_f32_e32 v22, v22, v143
	v_lshlrev_b32_e32 v144, 16, v162
	v_mul_f32_e32 v22, v22, v144
	v_and_b32_e32 v143, 0xffff0000, v158
	v_mul_f32_e32 v23, v23, v143
	v_and_b32_e32 v144, 0xffff0000, v162
	v_mul_f32_e32 v23, v23, v144
	v_lshlrev_b32_e32 v143, 16, v159
	v_mul_f32_e32 v24, v24, v143
	v_lshlrev_b32_e32 v144, 16, v163
	v_mul_f32_e32 v24, v24, v144
	v_and_b32_e32 v143, 0xffff0000, v159
	v_mul_f32_e32 v25, v25, v143
	v_and_b32_e32 v144, 0xffff0000, v163
	v_mul_f32_e32 v25, v25, v144
	v_lshlrev_b32_e32 v143, 16, v160
	v_mul_f32_e32 v18, v18, v143
	v_lshlrev_b32_e32 v144, 16, v164
	v_mul_f32_e32 v18, v18, v144
	v_and_b32_e32 v143, 0xffff0000, v160
	v_mul_f32_e32 v19, v19, v143
	v_and_b32_e32 v144, 0xffff0000, v164
	v_mul_f32_e32 v19, v19, v144
	v_lshlrev_b32_e32 v143, 16, v161
	v_mul_f32_e32 v20, v20, v143
	v_lshlrev_b32_e32 v144, 16, v165
	v_mul_f32_e32 v20, v20, v144
	v_and_b32_e32 v143, 0xffff0000, v161
	v_mul_f32_e32 v21, v21, v143
	v_and_b32_e32 v144, 0xffff0000, v165
	v_mul_f32_e32 v21, v21, v144
	v_cvt_pk_bf16_f32 v158, v22, v23
	v_cvt_pk_bf16_f32 v159, v24, v25
	v_cvt_pk_bf16_f32 v160, v18, v19
	v_cvt_pk_bf16_f32 v161, v20, v21
	global_store_dwordx4 v142, v[158:161], s[16:17] offset:256
	v_add_u32_e32 v142, 0x8000, v142
	s_waitcnt vmcnt(7)
	v_pk_add_f32 v[14:15], v[14:15], v[224:225]
	v_pk_add_f32 v[16:17], v[16:17], v[226:227]
	v_pk_add_f32 v[10:11], v[10:11], v[228:229]
	v_pk_add_f32 v[12:13], v[12:13], v[230:231]
	v_mul_f32_e32 v14, 0xbfb8aa3b, v14
	v_mul_f32_e32 v15, 0xbfb8aa3b, v15
	v_mul_f32_e32 v16, 0xbfb8aa3b, v16
	v_mul_f32_e32 v17, 0xbfb8aa3b, v17
	v_mul_f32_e32 v10, 0xbfb8aa3b, v10
	v_mul_f32_e32 v11, 0xbfb8aa3b, v11
	v_mul_f32_e32 v12, 0xbfb8aa3b, v12
	v_mul_f32_e32 v13, 0xbfb8aa3b, v13
	v_exp_f32_e32 v14, v14
	v_exp_f32_e32 v15, v15
	v_exp_f32_e32 v16, v16
	v_exp_f32_e32 v17, v17
	v_exp_f32_e32 v10, v10
	v_exp_f32_e32 v11, v11
	v_exp_f32_e32 v12, v12
	v_exp_f32_e32 v13, v13
	v_add_f32_e32 v14, 1.0, v14
	v_add_f32_e32 v15, 1.0, v15
	v_add_f32_e32 v16, 1.0, v16
	v_add_f32_e32 v17, 1.0, v17
	v_add_f32_e32 v10, 1.0, v10
	v_add_f32_e32 v11, 1.0, v11
	v_add_f32_e32 v12, 1.0, v12
	v_add_f32_e32 v13, 1.0, v13
	v_rcp_f32_e32 v14, v14
	v_rcp_f32_e32 v15, v15
	v_rcp_f32_e32 v16, v16
	v_rcp_f32_e32 v17, v17
	v_rcp_f32_e32 v10, v10
	v_rcp_f32_e32 v11, v11
	v_rcp_f32_e32 v12, v12
	v_rcp_f32_e32 v13, v13
	v_lshlrev_b32_e32 v143, 16, v166
	v_mul_f32_e32 v14, v14, v143
	v_lshlrev_b32_e32 v144, 16, v170
	v_mul_f32_e32 v14, v14, v144
	v_and_b32_e32 v143, 0xffff0000, v166
	v_mul_f32_e32 v15, v15, v143
	v_and_b32_e32 v144, 0xffff0000, v170
	v_mul_f32_e32 v15, v15, v144
	v_lshlrev_b32_e32 v143, 16, v167
	v_mul_f32_e32 v16, v16, v143
	v_lshlrev_b32_e32 v144, 16, v171
	v_mul_f32_e32 v16, v16, v144
	v_and_b32_e32 v143, 0xffff0000, v167
	v_mul_f32_e32 v17, v17, v143
	v_and_b32_e32 v144, 0xffff0000, v171
	v_mul_f32_e32 v17, v17, v144
	v_lshlrev_b32_e32 v143, 16, v168
	v_mul_f32_e32 v10, v10, v143
	v_lshlrev_b32_e32 v144, 16, v172
	v_mul_f32_e32 v10, v10, v144
	v_and_b32_e32 v143, 0xffff0000, v168
	v_mul_f32_e32 v11, v11, v143
	v_and_b32_e32 v144, 0xffff0000, v172
	v_mul_f32_e32 v11, v11, v144
	v_lshlrev_b32_e32 v143, 16, v169
	v_mul_f32_e32 v12, v12, v143
	v_lshlrev_b32_e32 v144, 16, v173
	v_mul_f32_e32 v12, v12, v144
	v_and_b32_e32 v143, 0xffff0000, v169
	v_mul_f32_e32 v13, v13, v143
	v_and_b32_e32 v144, 0xffff0000, v173
	v_mul_f32_e32 v13, v13, v144
	v_cvt_pk_bf16_f32 v166, v14, v15
	v_cvt_pk_bf16_f32 v167, v16, v17
	v_cvt_pk_bf16_f32 v168, v10, v11
	v_cvt_pk_bf16_f32 v169, v12, v13
	global_store_dwordx4 v142, v[166:169], s[16:17]
	s_nop 0
	s_waitcnt vmcnt(5)
	v_pk_add_f32 v[6:7], v[6:7], v[232:233]
	v_pk_add_f32 v[8:9], v[8:9], v[234:235]
	v_pk_add_f32 v[2:3], v[2:3], v[236:237]
	v_pk_add_f32 v[4:5], v[4:5], v[238:239]
	v_mul_f32_e32 v6, 0xbfb8aa3b, v6
	v_mul_f32_e32 v7, 0xbfb8aa3b, v7
	v_mul_f32_e32 v8, 0xbfb8aa3b, v8
	v_mul_f32_e32 v9, 0xbfb8aa3b, v9
	v_mul_f32_e32 v2, 0xbfb8aa3b, v2
	v_mul_f32_e32 v3, 0xbfb8aa3b, v3
	v_mul_f32_e32 v4, 0xbfb8aa3b, v4
	v_mul_f32_e32 v5, 0xbfb8aa3b, v5
	v_exp_f32_e32 v6, v6
	v_exp_f32_e32 v7, v7
	v_exp_f32_e32 v8, v8
	v_exp_f32_e32 v9, v9
	v_exp_f32_e32 v2, v2
	v_exp_f32_e32 v3, v3
	v_exp_f32_e32 v4, v4
	v_exp_f32_e32 v5, v5
	v_add_f32_e32 v6, 1.0, v6
	v_add_f32_e32 v7, 1.0, v7
	v_add_f32_e32 v8, 1.0, v8
	v_add_f32_e32 v9, 1.0, v9
	v_add_f32_e32 v2, 1.0, v2
	v_add_f32_e32 v3, 1.0, v3
	v_add_f32_e32 v4, 1.0, v4
	v_add_f32_e32 v5, 1.0, v5
	v_rcp_f32_e32 v6, v6
	v_rcp_f32_e32 v7, v7
	v_rcp_f32_e32 v8, v8
	v_rcp_f32_e32 v9, v9
	v_rcp_f32_e32 v2, v2
	v_rcp_f32_e32 v3, v3
	v_rcp_f32_e32 v4, v4
	v_rcp_f32_e32 v5, v5
	v_lshlrev_b32_e32 v143, 16, v174
	v_mul_f32_e32 v6, v6, v143
	v_lshlrev_b32_e32 v144, 16, v178
	v_mul_f32_e32 v6, v6, v144
	v_and_b32_e32 v143, 0xffff0000, v174
	v_mul_f32_e32 v7, v7, v143
	v_and_b32_e32 v144, 0xffff0000, v178
	v_mul_f32_e32 v7, v7, v144
	v_lshlrev_b32_e32 v143, 16, v175
	v_mul_f32_e32 v8, v8, v143
	v_lshlrev_b32_e32 v144, 16, v179
	v_mul_f32_e32 v8, v8, v144
	v_and_b32_e32 v143, 0xffff0000, v175
	v_mul_f32_e32 v9, v9, v143
	v_and_b32_e32 v144, 0xffff0000, v179
	v_mul_f32_e32 v9, v9, v144
	v_lshlrev_b32_e32 v143, 16, v176
	v_mul_f32_e32 v2, v2, v143
	v_lshlrev_b32_e32 v144, 16, v180
	v_mul_f32_e32 v2, v2, v144
	v_and_b32_e32 v143, 0xffff0000, v176
	v_mul_f32_e32 v3, v3, v143
	v_and_b32_e32 v144, 0xffff0000, v180
	v_mul_f32_e32 v3, v3, v144
	v_lshlrev_b32_e32 v143, 16, v177
	v_mul_f32_e32 v4, v4, v143
	v_lshlrev_b32_e32 v144, 16, v181
	v_mul_f32_e32 v4, v4, v144
	v_and_b32_e32 v143, 0xffff0000, v177
	v_mul_f32_e32 v5, v5, v143
	v_and_b32_e32 v144, 0xffff0000, v181
	v_mul_f32_e32 v5, v5, v144
	v_cvt_pk_bf16_f32 v174, v6, v7
	v_cvt_pk_bf16_f32 v175, v8, v9
	v_cvt_pk_bf16_f32 v176, v2, v3
	v_cvt_pk_bf16_f32 v177, v4, v5
	global_store_dwordx4 v142, v[174:177], s[16:17] offset:256
	s_nop 0
	s_mov_b64 s[2:3], -1
	s_andn2_b64 vcc, exec, s[38:39]
	s_cbranch_vccnz .LBB0_842
	s_andn2_b64 vcc, exec, s[0:1]
	s_cbranch_vccnz .LBB0_841
	s_barrier
	s_branch .LBB0_841
